# conv split S=0x3c00 + DPP/row_bcast wave-sum (replaces 6-hop ds_bpermute butterfly) in RMSNorm P1 and final norm P12
# baseline (speedup 1.0000x reference)
.LBB0_245:
	v_pk_mul_f32 v[168:169], v[36:37], v[36:37]
	v_pk_mul_f32 v[170:171], v[32:33], v[32:33]
	v_pk_mul_f32 v[172:173], v[34:35], v[34:35]
	v_pk_mul_f32 v[174:175], v[30:31], v[30:31]
	v_mov_b32_e32 v176, v172
	v_mov_b32_e32 v177, v174
	v_mov_b32_e32 v174, v173
	v_mov_b32_e32 v172, v168
	v_mov_b32_e32 v173, v170
	v_mov_b32_e32 v170, v169
	v_pk_mul_f32 v[164:165], v[26:27], v[26:27]
	v_pk_mul_f32 v[166:167], v[28:29], v[28:29]
	v_pk_add_f32 v[168:169], v[176:177], v[174:175]
	v_pk_add_f32 v[170:171], v[172:173], v[170:171]
	v_mul_f32_e32 v2, v22, v22
	v_pk_add_f32 v[168:169], v[168:169], v[170:171]
	v_mov_b32_e32 v170, v164
	v_mov_b32_e32 v171, v167
	v_pk_mov_b32 v[164:165], v[164:165], v[166:167] op_sel:[1,0]
	v_pk_fma_f32 v[166:167], v[22:23], v[22:23], v[2:3] op_sel_hi:[1,1,0]
	v_pk_add_f32 v[164:165], v[164:165], v[170:171]
	v_mul_f32_e32 v2, v24, v24
	v_pk_add_f32 v[168:169], v[168:169], v[168:169] op_sel_hi:[0,1]
	v_pk_add_f32 v[164:165], v[164:165], v[164:165] op_sel_hi:[0,1]
	v_pk_fma_f32 v[170:171], v[24:25], v[24:25], v[2:3] op_sel_hi:[1,1,0]
	v_mul_f32_e32 v166, v18, v18
	v_mul_f32_e32 v170, v19, v19
	v_mul_f32_e32 v164, v20, v20
	v_mul_f32_e32 v168, v21, v21
	v_pk_mul_f32 v[4:5], v[14:15], v[14:15]
	v_pk_mul_f32 v[162:163], v[16:17], v[16:17]
	v_pk_add_f32 v[166:167], v[166:167], v[170:171]
	v_pk_add_f32 v[164:165], v[164:165], v[168:169]
	v_mul_f32_e32 v2, v10, v10
	v_pk_add_f32 v[164:165], v[166:167], v[164:165]
	v_mov_b32_e32 v166, v4
	v_mov_b32_e32 v167, v163
	v_pk_mov_b32 v[4:5], v[4:5], v[162:163] op_sel:[1,0]
	v_pk_fma_f32 v[162:163], v[10:11], v[10:11], v[2:3] op_sel_hi:[1,1,0]
	v_pk_add_f32 v[4:5], v[4:5], v[166:167]
	v_mul_f32_e32 v2, v12, v12
	v_pk_add_f32 v[164:165], v[164:165], v[164:165] op_sel_hi:[0,1]
	v_pk_add_f32 v[4:5], v[4:5], v[4:5] op_sel_hi:[0,1]
	v_pk_fma_f32 v[166:167], v[12:13], v[12:13], v[2:3] op_sel_hi:[1,1,0]
	v_mul_f32_e32 v162, v6, v6
	v_mul_f32_e32 v166, v7, v7
	v_mul_f32_e32 v4, v8, v8
	v_mul_f32_e32 v164, v9, v9
	v_pk_add_f32 v[162:163], v[162:163], v[166:167]
	v_pk_add_f32 v[4:5], v[4:5], v[164:165]
	s_nop 0
	v_pk_add_f32 v[4:5], v[162:163], v[4:5]
	s_nop 0
	v_add_f32_e32 v2, v4, v5
	s_nop 1
	v_add_f32_dpp v2, v2, v2 quad_perm:[1,0,3,2] row_mask:0xf bank_mask:0xf
	s_nop 1
	v_add_f32_dpp v2, v2, v2 quad_perm:[2,3,0,1] row_mask:0xf bank_mask:0xf
	s_nop 1
	v_add_f32_dpp v2, v2, v2 row_half_mirror row_mask:0xf bank_mask:0xf
	s_nop 1
	v_add_f32_dpp v2, v2, v2 row_mirror row_mask:0xf bank_mask:0xf
	s_nop 1
	v_add_f32_dpp v2, v2, v2 row_bcast:15 row_mask:0xa bank_mask:0xf
	s_nop 1
	v_add_f32_dpp v2, v2, v2 row_bcast:31 row_mask:0xc bank_mask:0xf
	s_nop 1
	v_readlane_b32 s98, v2, 63
	s_waitcnt lgkmcnt(0)
	v_mov_b32_e32 v2, s98
	v_fmamk_f32 v2, v2, 0x3a000000, v160
	v_mul_f32_e32 v4, 0x4f800000, v2
	v_cmp_gt_f32_e32 vcc, s23, v2
	s_nop 1
	v_cndmask_b32_e32 v2, v2, v4, vcc
	v_sqrt_f32_e32 v4, v2
	s_nop 0
	v_add_u32_e32 v5, -1, v4
	v_fma_f32 v162, -v5, v4, v2
	v_cmp_ge_f32_e64 s[4:5], 0, v162
	v_add_u32_e32 v162, 1, v4
	s_nop 0
	v_cndmask_b32_e64 v5, v4, v5, s[4:5]
	v_fma_f32 v4, -v162, v4, v2
	v_cmp_lt_f32_e64 s[4:5], 0, v4
	s_nop 1
	v_cndmask_b32_e64 v4, v5, v162, s[4:5]
	v_mul_f32_e32 v5, 0x37800000, v4
	v_cndmask_b32_e32 v4, v4, v5, vcc
	v_cmp_class_f32_e32 vcc, v2, v161
	s_nop 1
	v_cndmask_b32_e32 v2, v4, v2, vcc
	v_div_scale_f32 v4, s[0:1], v2, v2, 1.0
	v_rcp_f32_e32 v5, v4
	s_mov_b64 s[0:1], s[16:17]
	v_fma_f32 v162, -v4, v5, 1.0
	v_fmac_f32_e32 v5, v162, v5
	v_div_scale_f32 v162, vcc, 1.0, v2, 1.0
	v_mul_f32_e32 v163, v162, v5
	v_fma_f32 v164, -v4, v163, v162
	v_fmac_f32_e32 v163, v164, v5
	v_fma_f32 v4, -v4, v163, v162
	v_div_fmas_f32 v4, v4, v5, v163
	v_div_fixup_f32 v2, v4, v2, 1.0
	v_pk_mul_f32 v[4:5], v[34:35], v[2:3] op_sel_hi:[1,0]
	v_pk_mul_f32 v[34:35], v[36:37], v[2:3] op_sel_hi:[1,0]
	s_waitcnt vmcnt(7)
	v_pk_fma_f32 v[4:5], v[86:87], v[4:5], v[62:63]
	v_pk_fma_f32 v[34:35], v[88:89], v[34:35], v[64:65]
	v_bfe_u32 v36, v4, 16, 1
	v_add3_u32 v4, v4, v36, s22
	v_bfe_u32 v36, v5, 16, 1
	v_lshrrev_b32_e32 v4, 16, v4
	v_add3_u32 v5, v5, v36, s22
	v_and_or_b32 v4, v5, s24, v4
	v_bfe_u32 v5, v34, 16, 1
	v_add3_u32 v5, v34, v5, s22
	v_bfe_u32 v34, v35, 16, 1
	v_lshrrev_b32_e32 v5, 16, v5
	v_add3_u32 v34, v35, v34, s22
	v_and_or_b32 v5, v34, s24, v5
	global_store_dwordx2 v[146:147], v[4:5], off
	v_pk_mul_f32 v[4:5], v[30:31], v[2:3] op_sel_hi:[1,0]
	v_pk_mul_f32 v[30:31], v[32:33], v[2:3] op_sel_hi:[1,0]
	s_waitcnt vmcnt(7)
	v_pk_fma_f32 v[4:5], v[90:91], v[4:5], v[58:59]
	v_pk_fma_f32 v[30:31], v[92:93], v[30:31], v[60:61]
	v_bfe_u32 v32, v4, 16, 1
	v_add3_u32 v4, v4, v32, s22
	v_bfe_u32 v32, v5, 16, 1
	v_lshrrev_b32_e32 v4, 16, v4
	v_add3_u32 v5, v5, v32, s22
	v_and_or_b32 v4, v5, s24, v4
	v_bfe_u32 v5, v30, 16, 1
	v_add3_u32 v5, v30, v5, s22
	v_bfe_u32 v30, v31, 16, 1
	v_lshrrev_b32_e32 v5, 16, v5
	v_add3_u32 v30, v31, v30, s22
	v_and_or_b32 v5, v30, s24, v5
	global_store_dwordx2 v[146:147], v[4:5], off offset:512
	v_pk_mul_f32 v[4:5], v[26:27], v[2:3] op_sel_hi:[1,0]
	v_pk_mul_f32 v[26:27], v[28:29], v[2:3] op_sel_hi:[1,0]
	s_waitcnt vmcnt(7)
	v_pk_fma_f32 v[4:5], v[102:103], v[4:5], v[54:55]
	v_pk_fma_f32 v[26:27], v[104:105], v[26:27], v[56:57]
	v_bfe_u32 v28, v4, 16, 1
	v_add3_u32 v4, v4, v28, s22
	v_bfe_u32 v28, v5, 16, 1
	v_lshrrev_b32_e32 v4, 16, v4
	v_add3_u32 v5, v5, v28, s22
	v_and_or_b32 v4, v5, s24, v4
	v_bfe_u32 v5, v26, 16, 1
	v_add3_u32 v5, v26, v5, s22
	v_bfe_u32 v26, v27, 16, 1
	v_lshrrev_b32_e32 v5, 16, v5
	v_add3_u32 v26, v27, v26, s22
	v_and_or_b32 v5, v26, s24, v5
	global_store_dwordx2 v[146:147], v[4:5], off offset:1024
	v_pk_mul_f32 v[4:5], v[22:23], v[2:3] op_sel_hi:[1,0]
	v_pk_mul_f32 v[22:23], v[24:25], v[2:3] op_sel_hi:[1,0]
	s_waitcnt vmcnt(7)
	v_pk_fma_f32 v[4:5], v[114:115], v[4:5], v[50:51]
	v_pk_fma_f32 v[22:23], v[116:117], v[22:23], v[52:53]
	v_bfe_u32 v24, v4, 16, 1
	v_add3_u32 v4, v4, v24, s22
	v_bfe_u32 v24, v5, 16, 1
	v_lshrrev_b32_e32 v4, 16, v4
	v_add3_u32 v5, v5, v24, s22
	v_and_or_b32 v4, v5, s24, v4
	v_bfe_u32 v5, v22, 16, 1
	v_add3_u32 v5, v22, v5, s22
	v_bfe_u32 v22, v23, 16, 1
	v_lshrrev_b32_e32 v5, 16, v5
	v_add3_u32 v22, v23, v22, s22
	v_and_or_b32 v5, v22, s24, v5
	global_store_dwordx2 v[146:147], v[4:5], off offset:1536
	v_pk_mul_f32 v[4:5], v[18:19], v[2:3] op_sel_hi:[1,0]
	v_pk_mul_f32 v[18:19], v[20:21], v[2:3] op_sel_hi:[1,0]
	s_waitcnt vmcnt(7)
	v_pk_fma_f32 v[4:5], v[118:119], v[4:5], v[46:47]
	v_pk_fma_f32 v[18:19], v[120:121], v[18:19], v[48:49]
	v_bfe_u32 v20, v4, 16, 1
	v_add3_u32 v4, v4, v20, s22
	v_bfe_u32 v20, v5, 16, 1
	v_lshrrev_b32_e32 v4, 16, v4
	v_add3_u32 v5, v5, v20, s22
	v_and_or_b32 v4, v5, s24, v4
	v_bfe_u32 v5, v18, 16, 1
	v_add3_u32 v5, v18, v5, s22
	v_bfe_u32 v18, v19, 16, 1
	v_lshrrev_b32_e32 v5, 16, v5
	v_add3_u32 v18, v19, v18, s22
	v_and_or_b32 v5, v18, s24, v5
	global_store_dwordx2 v[146:147], v[4:5], off offset:2048
	v_pk_mul_f32 v[4:5], v[14:15], v[2:3] op_sel_hi:[1,0]
	v_pk_mul_f32 v[14:15], v[16:17], v[2:3] op_sel_hi:[1,0]
	s_waitcnt vmcnt(7)
	v_pk_fma_f32 v[4:5], v[122:123], v[4:5], v[42:43]
	v_pk_fma_f32 v[14:15], v[124:125], v[14:15], v[44:45]
	v_bfe_u32 v16, v4, 16, 1
	v_add3_u32 v4, v4, v16, s22
	v_bfe_u32 v16, v5, 16, 1
	v_lshrrev_b32_e32 v4, 16, v4
	v_add3_u32 v5, v5, v16, s22
	v_and_or_b32 v4, v5, s24, v4
	v_bfe_u32 v5, v14, 16, 1
	v_add3_u32 v5, v14, v5, s22
	v_bfe_u32 v14, v15, 16, 1
	v_lshrrev_b32_e32 v5, 16, v5
	v_add3_u32 v14, v15, v14, s22
	v_and_or_b32 v5, v14, s24, v5
	global_store_dwordx2 v[146:147], v[4:5], off offset:2560
	v_pk_mul_f32 v[4:5], v[10:11], v[2:3] op_sel_hi:[1,0]
	v_pk_mul_f32 v[10:11], v[12:13], v[2:3] op_sel_hi:[1,0]
	s_waitcnt vmcnt(7)
	v_pk_fma_f32 v[4:5], v[126:127], v[4:5], v[38:39]
	v_pk_fma_f32 v[10:11], v[128:129], v[10:11], v[40:41]
	v_bfe_u32 v12, v4, 16, 1
	v_add3_u32 v4, v4, v12, s22
	v_bfe_u32 v12, v5, 16, 1
	v_lshrrev_b32_e32 v4, 16, v4
	v_add3_u32 v5, v5, v12, s22
	v_and_or_b32 v4, v5, s24, v4
	v_bfe_u32 v5, v10, 16, 1
	v_add3_u32 v5, v10, v5, s22
	v_bfe_u32 v10, v11, 16, 1
	v_lshrrev_b32_e32 v5, 16, v5
	v_add3_u32 v10, v11, v10, s22
	v_and_or_b32 v5, v10, s24, v5
	global_store_dwordx2 v[146:147], v[4:5], off offset:3072
	v_pk_mul_f32 v[4:5], v[6:7], v[2:3] op_sel_hi:[1,0]
	v_pk_mul_f32 v[6:7], v[8:9], v[2:3] op_sel_hi:[1,0]
	s_waitcnt vmcnt(7)
	v_pk_fma_f32 v[4:5], v[130:131], v[4:5], v[66:67]
	v_pk_fma_f32 v[6:7], v[132:133], v[6:7], v[68:69]
	v_bfe_u32 v2, v4, 16, 1
	v_add3_u32 v2, v4, v2, s22
	v_bfe_u32 v4, v5, 16, 1
	v_lshrrev_b32_e32 v2, 16, v2
	v_add3_u32 v4, v5, v4, s22
	v_and_or_b32 v4, v4, s24, v2
	v_bfe_u32 v2, v6, 16, 1
	v_add3_u32 v2, v6, v2, s22
	v_bfe_u32 v5, v7, 16, 1
	v_lshrrev_b32_e32 v2, 16, v2
	v_add3_u32 v5, v7, v5, s22
	v_and_or_b32 v5, v5, s24, v2
	global_store_dwordx2 v[146:147], v[4:5], off offset:3584
	v_lshl_add_u64 v[146:147], v[146:147], 0, s[14:15]
	s_andn2_b64 vcc, exec, s[18:19]
	v_mov_b32_e32 v34, v70
	v_mov_b32_e32 v35, v71
	v_mov_b32_e32 v36, v72
	v_mov_b32_e32 v37, v73
	v_mov_b32_e32 v30, v74
	v_mov_b32_e32 v31, v75
	v_mov_b32_e32 v32, v76
	v_mov_b32_e32 v33, v77
	v_mov_b32_e32 v26, v78
	v_mov_b32_e32 v27, v79
	v_mov_b32_e32 v28, v80
	v_mov_b32_e32 v29, v81
	v_mov_b32_e32 v22, v82
	v_mov_b32_e32 v23, v83
	v_mov_b32_e32 v24, v84
	v_mov_b32_e32 v25, v85
	v_mov_b32_e32 v18, v94
	v_mov_b32_e32 v19, v95
	v_mov_b32_e32 v20, v96
	v_mov_b32_e32 v21, v97
	v_mov_b32_e32 v14, v98
	v_mov_b32_e32 v15, v99
	v_mov_b32_e32 v16, v100
	v_mov_b32_e32 v17, v101
	v_mov_b32_e32 v10, v106
	v_mov_b32_e32 v11, v107
	v_mov_b32_e32 v12, v108
	v_mov_b32_e32 v13, v109
	v_mov_b32_e32 v6, v110
	v_mov_b32_e32 v7, v111
	v_mov_b32_e32 v8, v112
	v_mov_b32_e32 v9, v113
	s_cbranch_vccz .LBB0_252

.LBB0_1301:
	v_pk_mul_f32 v[100:101], v[82:83], v[82:83]
	v_pk_mul_f32 v[102:103], v[78:79], v[78:79]
	v_pk_mul_f32 v[96:97], v[84:85], v[84:85]
	v_pk_mul_f32 v[98:99], v[80:81], v[80:81]
	v_mov_b32_e32 v104, v100
	v_mov_b32_e32 v105, v102
	v_mov_b32_e32 v102, v101
	v_pk_mul_f32 v[92:93], v[76:77], v[76:77]
	v_pk_mul_f32 v[94:95], v[74:75], v[74:75]
	v_pk_add_f32 v[100:101], v[104:105], v[102:103]
	v_mov_b32_e32 v102, v96
	v_mov_b32_e32 v103, v98
	v_mov_b32_e32 v98, v97
	v_pk_add_f32 v[96:97], v[102:103], v[98:99]
	v_pk_mov_b32 v[98:99], v[94:95], v[92:93] op_sel:[1,0]
	v_mov_b32_e32 v95, v93
	v_pk_add_f32 v[92:93], v[98:99], v[94:95]
	v_pk_add_f32 v[96:97], v[100:101], v[96:97]
	v_pk_add_f32 v[92:93], v[92:93], v[92:93] op_sel_hi:[0,1]
	v_mul_f32_e32 v92, v66, v66
	v_pk_fma_f32 v[94:95], v[66:67], v[66:67], v[92:93] op_sel_hi:[1,1,0]
	v_mul_f32_e32 v92, v68, v68
	v_pk_add_f32 v[96:97], v[96:97], v[96:97] op_sel_hi:[0,1]
	v_pk_fma_f32 v[98:99], v[68:69], v[68:69], v[92:93] op_sel_hi:[1,1,0]
	v_mul_f32_e32 v94, v72, v72
	v_mul_f32_e32 v98, v73, v73
	v_mul_f32_e32 v92, v70, v70
	v_mul_f32_e32 v96, v71, v71
	v_pk_mul_f32 v[88:89], v[64:65], v[64:65]
	v_pk_mul_f32 v[90:91], v[62:63], v[62:63]
	v_pk_add_f32 v[94:95], v[94:95], v[98:99]
	v_pk_add_f32 v[92:93], v[92:93], v[96:97]
	v_lshl_add_u64 v[34:35], v[34:35], 0, s[6:7]
	v_pk_add_f32 v[92:93], v[94:95], v[92:93]
	v_pk_mov_b32 v[94:95], v[90:91], v[88:89] op_sel:[1,0]
	v_mov_b32_e32 v91, v89
	v_pk_add_f32 v[88:89], v[94:95], v[90:91]
	v_pk_add_f32 v[92:93], v[92:93], v[92:93] op_sel_hi:[0,1]
	v_pk_add_f32 v[88:89], v[88:89], v[88:89] op_sel_hi:[0,1]
	v_mul_f32_e32 v88, v58, v58
	v_pk_fma_f32 v[90:91], v[58:59], v[58:59], v[88:89] op_sel_hi:[1,1,0]
	v_mul_f32_e32 v88, v60, v60
	v_pk_fma_f32 v[94:95], v[60:61], v[60:61], v[88:89] op_sel_hi:[1,1,0]
	v_mul_f32_e32 v90, v56, v56
	v_mul_f32_e32 v94, v57, v57
	v_mul_f32_e32 v88, v54, v54
	v_mul_f32_e32 v92, v55, v55
	v_pk_add_f32 v[90:91], v[90:91], v[94:95]
	v_pk_add_f32 v[88:89], v[88:89], v[92:93]
	s_mov_b32 s10, s11
	v_pk_add_f32 v[88:89], v[90:91], v[88:89]
	s_nop 0
	v_add_f32_e32 v88, v88, v89
	s_nop 1
	v_add_f32_dpp v88, v88, v88 quad_perm:[1,0,3,2] row_mask:0xf bank_mask:0xf
	s_nop 1
	v_add_f32_dpp v88, v88, v88 quad_perm:[2,3,0,1] row_mask:0xf bank_mask:0xf
	s_nop 1
	v_add_f32_dpp v88, v88, v88 row_half_mirror row_mask:0xf bank_mask:0xf
	s_nop 1
	v_add_f32_dpp v88, v88, v88 row_mirror row_mask:0xf bank_mask:0xf
	s_nop 1
	v_add_f32_dpp v88, v88, v88 row_bcast:15 row_mask:0xa bank_mask:0xf
	s_nop 1
	v_add_f32_dpp v88, v88, v88 row_bcast:31 row_mask:0xc bank_mask:0xf
	s_nop 1
	v_readlane_b32 s98, v88, 63
	s_waitcnt lgkmcnt(0)
	v_mov_b32_e32 v88, s98
	v_fmamk_f32 v88, v88, 0x3a000000, v86
	v_mul_f32_e32 v89, 0x4f800000, v88
	v_cmp_gt_f32_e32 vcc, s17, v88
	s_nop 1
	v_cndmask_b32_e32 v88, v88, v89, vcc
	v_sqrt_f32_e32 v89, v88
	s_nop 0
	v_add_u32_e32 v90, -1, v89
	v_fma_f32 v91, -v90, v89, v88
	v_cmp_ge_f32_e64 s[0:1], 0, v91
	v_add_u32_e32 v91, 1, v89
	s_nop 0
	v_cndmask_b32_e64 v90, v89, v90, s[0:1]
	v_fma_f32 v89, -v91, v89, v88
	v_cmp_lt_f32_e64 s[0:1], 0, v89
	s_nop 1
	v_cndmask_b32_e64 v89, v90, v91, s[0:1]
	v_mul_f32_e32 v90, 0x37800000, v89
	v_cndmask_b32_e32 v89, v89, v90, vcc
	v_cmp_class_f32_e32 vcc, v88, v87
	s_nop 1
	v_cndmask_b32_e32 v88, v89, v88, vcc
	v_div_scale_f32 v89, s[0:1], v88, v88, 1.0
	v_rcp_f32_e32 v90, v89
	s_nop 0
	v_fma_f32 v91, -v89, v90, 1.0
	v_fmac_f32_e32 v90, v91, v90
	v_div_scale_f32 v91, vcc, 1.0, v88, 1.0
	v_mul_f32_e32 v92, v91, v90
	v_fma_f32 v93, -v89, v92, v91
	v_fmac_f32_e32 v92, v93, v90
	v_fma_f32 v89, -v89, v92, v91
	v_div_fmas_f32 v89, v89, v90, v92
	v_div_fixup_f32 v88, v89, v88, 1.0
	v_pk_mul_f32 v[66:67], v[66:67], v[88:89] op_sel_hi:[1,0]
	v_pk_mul_f32 v[68:69], v[68:69], v[88:89] op_sel_hi:[1,0]
	v_pk_mul_f32 v[58:59], v[58:59], v[88:89] op_sel_hi:[1,0]
	v_pk_mul_f32 v[60:61], v[60:61], v[88:89] op_sel_hi:[1,0]
	v_pk_mul_f32 v[68:69], v[16:17], v[68:69]
	v_pk_mul_f32 v[66:67], v[14:15], v[66:67]
	s_waitcnt vmcnt(1)
	v_pk_mul_f32 v[60:61], v[28:29], v[60:61]
	v_pk_mul_f32 v[58:59], v[26:27], v[58:59]
	v_pk_mul_f32 v[82:83], v[82:83], v[88:89] op_sel_hi:[1,0]
	v_pk_mul_f32 v[84:85], v[84:85], v[88:89] op_sel_hi:[1,0]
	v_pk_mul_f32 v[78:79], v[78:79], v[88:89] op_sel_hi:[1,0]
	v_pk_mul_f32 v[80:81], v[80:81], v[88:89] op_sel_hi:[1,0]
	v_pk_mul_f32 v[74:75], v[74:75], v[88:89] op_sel_hi:[1,0]
	v_pk_mul_f32 v[76:77], v[76:77], v[88:89] op_sel_hi:[1,0]
	global_store_dwordx4 v[36:37], v[66:69], off offset:-1024 nt
	v_pk_mul_f32 v[62:63], v[62:63], v[88:89] op_sel_hi:[1,0]
	v_pk_mul_f32 v[64:65], v[64:65], v[88:89] op_sel_hi:[1,0]
	v_pk_mul_f32 v[66:67], v[72:73], v[88:89] op_sel_hi:[1,0]
	v_pk_mul_f32 v[68:69], v[70:71], v[88:89] op_sel_hi:[1,0]
	global_store_dwordx4 v[36:37], v[58:61], off offset:2048 nt
	v_pk_mul_f32 v[54:55], v[54:55], v[88:89] op_sel_hi:[1,0]
	v_pk_mul_f32 v[84:85], v[4:5], v[84:85]
	v_pk_mul_f32 v[58:59], v[56:57], v[88:89] op_sel_hi:[1,0]
	v_pk_mul_f32 v[82:83], v[2:3], v[82:83]
	v_pk_mul_f32 v[80:81], v[8:9], v[80:81]
	v_pk_mul_f32 v[78:79], v[6:7], v[78:79]
	v_pk_mul_f32 v[76:77], v[12:13], v[76:77]
	v_pk_mul_f32 v[74:75], v[10:11], v[74:75]
	v_pk_mul_f32 v[68:69], v[20:21], v[68:69]
	v_pk_mul_f32 v[66:67], v[18:19], v[66:67]
	v_pk_mul_f32 v[64:65], v[24:25], v[64:65]
	v_pk_mul_f32 v[62:63], v[22:23], v[62:63]
	s_waitcnt vmcnt(2)
	v_pk_mul_f32 v[56:57], v[32:33], v[54:55]
	v_pk_mul_f32 v[54:55], v[30:31], v[58:59]
	global_store_dwordx4 v[36:37], v[82:85], off offset:-4096 nt
	global_store_dwordx4 v[36:37], v[78:81], off offset:-3072 nt
	global_store_dwordx4 v[36:37], v[74:77], off offset:-2048 nt
	global_store_dwordx4 v[36:37], v[66:69], off nt
	global_store_dwordx4 v[36:37], v[62:65], off offset:1024 nt
	global_store_dwordx4 v[36:37], v[54:57], off offset:3072 nt
	v_lshl_add_u64 v[36:37], v[36:37], 0, s[4:5]
	s_andn2_b64 vcc, exec, s[8:9]
	v_mov_b64_e32 v[54:55], v[38:39]
	v_mov_b64_e32 v[56:57], v[40:41]
	v_mov_b64_e32 v[58:59], v[42:43]
	v_mov_b64_e32 v[60:61], v[44:45]
	v_mov_b64_e32 v[62:63], v[46:47]
	v_mov_b64_e32 v[64:65], v[48:49]
	v_mov_b64_e32 v[68:69], v[50:51]
	v_mov_b64_e32 v[66:67], v[52:53]
	s_cbranch_vccz .LBB0_1306
